# logf skinny GEMM K loop software-pipelined (2x8 k-steps in flight) on top of RG wB load batching
# speedup vs baseline: 1.0107x; 1.0070x over previous
.LBB0_218:
	v_add_co_u32_e32 v16, vcc, 0xa000000, v14
	s_nop 1
	v_addc_co_u32_e32 v17, vcc, 0, v15, vcc
	v_mov_b32_e32 v18, v12
	v_mov_b32_e32 v19, v13
	global_load_dwordx4 v[32:35], v[16:17], off
	global_load_dwordx4 v[64:67], v[18:19], off offset:-512
	global_load_dwordx4 v[36:39], v[16:17], off offset:64
	global_load_dwordx4 v[68:71], v[18:19], off offset:-448
	global_load_dwordx4 v[40:43], v[16:17], off offset:128
	global_load_dwordx4 v[72:75], v[18:19], off offset:-384
	global_load_dwordx4 v[44:47], v[16:17], off offset:192
	global_load_dwordx4 v[76:79], v[18:19], off offset:-320
	global_load_dwordx4 v[48:51], v[16:17], off offset:256
	global_load_dwordx4 v[80:83], v[18:19], off offset:-256
	global_load_dwordx4 v[52:55], v[16:17], off offset:320
	global_load_dwordx4 v[84:87], v[18:19], off offset:-192
	global_load_dwordx4 v[56:59], v[16:17], off offset:384
	global_load_dwordx4 v[88:91], v[18:19], off offset:-128
	global_load_dwordx4 v[60:63], v[16:17], off offset:448
	global_load_dwordx4 v[92:95], v[18:19], off offset:-64
	global_load_dwordx4 v[100:103], v[16:17], off offset:512
	global_load_dwordx4 v[132:135], v[18:19], off
	global_load_dwordx4 v[104:107], v[16:17], off offset:576
	global_load_dwordx4 v[136:139], v[18:19], off offset:64
	global_load_dwordx4 v[108:111], v[16:17], off offset:640
	global_load_dwordx4 v[140:143], v[18:19], off offset:128
	global_load_dwordx4 v[112:115], v[16:17], off offset:704
	global_load_dwordx4 v[144:147], v[18:19], off offset:192
	global_load_dwordx4 v[116:119], v[16:17], off offset:768
	global_load_dwordx4 v[148:151], v[18:19], off offset:256
	global_load_dwordx4 v[120:123], v[16:17], off offset:832
	global_load_dwordx4 v[152:155], v[18:19], off offset:320
	global_load_dwordx4 v[124:127], v[16:17], off offset:896
	global_load_dwordx4 v[156:159], v[18:19], off offset:384
	global_load_dwordx4 v[128:131], v[16:17], off offset:960
	global_load_dwordx4 v[160:163], v[18:19], off offset:448
	s_waitcnt vmcnt(16)
	v_mfma_f32_16x16x32_bf16 v[0:3], v[32:35], v[64:67], v[0:3]
	v_mfma_f32_16x16x32_bf16 v[0:3], v[36:39], v[68:71], v[0:3]
	v_mfma_f32_16x16x32_bf16 v[0:3], v[40:43], v[72:75], v[0:3]
	v_mfma_f32_16x16x32_bf16 v[0:3], v[44:47], v[76:79], v[0:3]
	v_mfma_f32_16x16x32_bf16 v[0:3], v[48:51], v[80:83], v[0:3]
	v_mfma_f32_16x16x32_bf16 v[0:3], v[52:55], v[84:87], v[0:3]
	v_mfma_f32_16x16x32_bf16 v[0:3], v[56:59], v[88:91], v[0:3]
	v_mfma_f32_16x16x32_bf16 v[0:3], v[60:63], v[92:95], v[0:3]
	global_load_dwordx4 v[32:35], v[16:17], off offset:1024
	global_load_dwordx4 v[64:67], v[18:19], off offset:512
	global_load_dwordx4 v[36:39], v[16:17], off offset:1088
	global_load_dwordx4 v[68:71], v[18:19], off offset:576
	global_load_dwordx4 v[40:43], v[16:17], off offset:1152
	global_load_dwordx4 v[72:75], v[18:19], off offset:640
	global_load_dwordx4 v[44:47], v[16:17], off offset:1216
	global_load_dwordx4 v[76:79], v[18:19], off offset:704
	global_load_dwordx4 v[48:51], v[16:17], off offset:1280
	global_load_dwordx4 v[80:83], v[18:19], off offset:768
	global_load_dwordx4 v[52:55], v[16:17], off offset:1344
	global_load_dwordx4 v[84:87], v[18:19], off offset:832
	global_load_dwordx4 v[56:59], v[16:17], off offset:1408
	global_load_dwordx4 v[88:91], v[18:19], off offset:896
	global_load_dwordx4 v[60:63], v[16:17], off offset:1472
	global_load_dwordx4 v[92:95], v[18:19], off offset:960
	s_waitcnt vmcnt(16)
	v_mfma_f32_16x16x32_bf16 v[0:3], v[100:103], v[132:135], v[0:3]
	v_mfma_f32_16x16x32_bf16 v[0:3], v[104:107], v[136:139], v[0:3]
	v_mfma_f32_16x16x32_bf16 v[0:3], v[108:111], v[140:143], v[0:3]
	v_mfma_f32_16x16x32_bf16 v[0:3], v[112:115], v[144:147], v[0:3]
	v_mfma_f32_16x16x32_bf16 v[0:3], v[116:119], v[148:151], v[0:3]
	v_mfma_f32_16x16x32_bf16 v[0:3], v[120:123], v[152:155], v[0:3]
	v_mfma_f32_16x16x32_bf16 v[0:3], v[124:127], v[156:159], v[0:3]
	v_mfma_f32_16x16x32_bf16 v[0:3], v[128:131], v[160:163], v[0:3]
	global_load_dwordx4 v[100:103], v[16:17], off offset:1536
	global_load_dwordx4 v[132:135], v[18:19], off offset:1024
	global_load_dwordx4 v[104:107], v[16:17], off offset:1600
	global_load_dwordx4 v[136:139], v[18:19], off offset:1088
	global_load_dwordx4 v[108:111], v[16:17], off offset:1664
	global_load_dwordx4 v[140:143], v[18:19], off offset:1152
	global_load_dwordx4 v[112:115], v[16:17], off offset:1728
	global_load_dwordx4 v[144:147], v[18:19], off offset:1216
	global_load_dwordx4 v[116:119], v[16:17], off offset:1792
	global_load_dwordx4 v[148:151], v[18:19], off offset:1280
	global_load_dwordx4 v[120:123], v[16:17], off offset:1856
	global_load_dwordx4 v[152:155], v[18:19], off offset:1344
	global_load_dwordx4 v[124:127], v[16:17], off offset:1920
	global_load_dwordx4 v[156:159], v[18:19], off offset:1408
	global_load_dwordx4 v[128:131], v[16:17], off offset:1984
	global_load_dwordx4 v[160:163], v[18:19], off offset:1472
	s_waitcnt vmcnt(16)
	v_mfma_f32_16x16x32_bf16 v[0:3], v[32:35], v[64:67], v[0:3]
	v_mfma_f32_16x16x32_bf16 v[0:3], v[36:39], v[68:71], v[0:3]
	v_mfma_f32_16x16x32_bf16 v[0:3], v[40:43], v[72:75], v[0:3]
	v_mfma_f32_16x16x32_bf16 v[0:3], v[44:47], v[76:79], v[0:3]
	v_mfma_f32_16x16x32_bf16 v[0:3], v[48:51], v[80:83], v[0:3]
	v_mfma_f32_16x16x32_bf16 v[0:3], v[52:55], v[84:87], v[0:3]
	v_mfma_f32_16x16x32_bf16 v[0:3], v[56:59], v[88:91], v[0:3]
	v_mfma_f32_16x16x32_bf16 v[0:3], v[60:63], v[92:95], v[0:3]
	s_waitcnt vmcnt(0)
	v_mfma_f32_16x16x32_bf16 v[0:3], v[100:103], v[132:135], v[0:3]
	v_mfma_f32_16x16x32_bf16 v[0:3], v[104:107], v[136:139], v[0:3]
	v_mfma_f32_16x16x32_bf16 v[0:3], v[108:111], v[140:143], v[0:3]
	v_mfma_f32_16x16x32_bf16 v[0:3], v[112:115], v[144:147], v[0:3]
	v_mfma_f32_16x16x32_bf16 v[0:3], v[116:119], v[148:151], v[0:3]
	v_mfma_f32_16x16x32_bf16 v[0:3], v[120:123], v[152:155], v[0:3]
	v_mfma_f32_16x16x32_bf16 v[0:3], v[124:127], v[156:159], v[0:3]
	v_mfma_f32_16x16x32_bf16 v[0:3], v[128:131], v[160:163], v[0:3]
	s_and_saveexec_b64 s[70:71], s[6:7]
	s_cbranch_execz .LBB0_216
	s_lshl_b32 s0, s5, 4
	v_or_b32_e32 v16, s0, v22
	v_ashrrev_i32_e32 v17, 31, v16
	v_lshlrev_b64 v[14:15], 6, v[16:17]
	v_lshl_add_u64 v[14:15], s[18:19], 0, v[14:15]
	global_load_dwordx4 v[18:21], v[14:15], off
	global_load_dwordx4 v[24:27], v[14:15], off offset:16
	global_load_dwordx4 v[28:31], v[14:15], off offset:32
	global_load_dwordx4 v[32:35], v[14:15], off offset:48
	global_load_dword v11, v[4:5], off
	v_bitop3_b32 v14, s0, v216, v22 bitop3:0xc8
	v_lshlrev_b32_e32 v98, 2, v14
	s_ashr_i32 s72, s5, 8
	s_ashr_i32 s73, s72, 31
	s_lshl_b64 s[0:1], s[72:73], 17
	v_or_b32_e32 v36, 1, v16
	v_ashrrev_i32_e32 v37, 31, v36
	s_waitcnt vmcnt(3)
	v_pk_add_f32 v[14:15], v[20:21], v[26:27]
	v_pk_add_f32 v[18:19], v[18:19], v[24:25]
	s_waitcnt vmcnt(1)
	v_pk_add_f32 v[20:21], v[30:31], v[34:35]
	v_pk_add_f32 v[24:25], v[28:29], v[32:33]
	v_pk_add_f32 v[14:15], v[14:15], v[20:21]
	v_pk_add_f32 v[18:19], v[18:19], v[24:25]
	s_nop 0
	v_pk_mov_b32 v[20:21], v[18:19], v[14:15] op_sel:[1,0]
	v_mov_b32_e32 v19, v15
	v_pk_add_f32 v[14:15], v[20:21], v[18:19]
	v_lshlrev_b64 v[20:21], 6, v[36:37]
	v_add_f32_e32 v14, v14, v15
	v_fmamk_f32 v14, v14, 0x3a800000, v199
	v_rsq_f32_e32 v17, v14
	v_lshl_add_u64 v[14:15], v[6:7], 0, s[0:1]
	v_lshl_add_u64 v[18:19], v[14:15], 0, v[98:99]
	v_lshl_add_u64 v[20:21], s[18:19], 0, v[20:21]
	s_waitcnt vmcnt(0)
	v_fma_f32 v0, v0, v17, v11
	v_mul_f32_e64 v17, |v0|, s40
	v_exp_f32_e32 v17, v17
	v_max_f32_e64 v0, -v0, 0
	s_movk_i32 s0, 0xffd
	v_or_b32_e32 v36, 2, v16
	v_add_f32_e32 v23, 1.0, v17
	v_add_f32_e32 v26, -1.0, v23
	v_frexp_mant_f32_e32 v27, v23
	v_cvt_f64_f32_e32 v[24:25], v23
	v_sub_f32_e32 v28, v26, v23
	v_frexp_exp_i32_f64_e32 v24, v[24:25]
	v_cmp_gt_f32_e32 vcc, s35, v27
	v_sub_f32_e32 v26, v17, v26
	v_add_f32_e32 v25, 1.0, v28
	v_subbrev_co_u32_e32 v24, vcc, 0, v24, vcc
	v_add_f32_e32 v25, v26, v25
	v_sub_u32_e32 v26, 0, v24
	v_cvt_f32_i32_e32 v24, v24
	v_ldexp_f32 v23, v23, v26
	v_ldexp_f32 v25, v25, v26
	v_add_f32_e32 v26, -1.0, v23
	v_add_f32_e32 v27, 1.0, v23
	v_add_f32_e32 v28, 1.0, v26
	v_add_f32_e32 v29, -1.0, v27
	v_sub_f32_e32 v28, v23, v28
	v_sub_f32_e32 v23, v23, v29
	v_mul_f32_e32 v29, 0x3f317218, v24
	v_add_f32_e32 v28, v25, v28
	v_add_f32_e32 v23, v25, v23
	v_fma_f32 v25, v24, s36, -v29
	v_add_f32_e32 v30, v26, v28
	v_add_f32_e32 v31, v27, v23
	v_fmac_f32_e32 v25, 0xb102e308, v24
	v_sub_f32_e32 v24, v30, v26
	v_sub_f32_e32 v26, v31, v27
	v_rcp_f32_e32 v27, v31
	v_add_f32_e32 v32, v29, v25
	v_sub_f32_e32 v23, v23, v26
	v_sub_f32_e32 v26, v32, v29
	v_sub_f32_e32 v25, v25, v26
	v_mul_f32_e32 v26, v30, v27
	v_sub_f32_e32 v24, v28, v24
	v_mul_f32_e32 v28, v31, v26
	v_fma_f32 v29, v26, v31, -v28
	v_fmac_f32_e32 v29, v26, v23
	v_add_f32_e32 v33, v28, v29
	v_sub_f32_e32 v34, v30, v33
	v_sub_f32_e32 v28, v33, v28
	v_sub_f32_e32 v30, v30, v34
	v_sub_f32_e32 v28, v28, v29
	v_sub_f32_e32 v29, v30, v33
	v_add_f32_e32 v24, v24, v29
	v_add_f32_e32 v24, v28, v24
	v_add_f32_e32 v28, v34, v24
	v_mul_f32_e32 v29, v27, v28
	v_sub_f32_e32 v30, v34, v28
	v_mul_f32_e32 v33, v31, v29
	v_add_f32_e32 v24, v24, v30
	v_add_f32_e32 v30, v26, v29
	v_fma_f32 v31, v29, v31, -v33
	v_sub_f32_e32 v26, v30, v26
	v_fmac_f32_e32 v31, v29, v23
	v_sub_f32_e32 v23, v29, v26
	v_add_f32_e32 v26, v33, v31
	v_sub_f32_e32 v29, v26, v33
	v_sub_f32_e32 v33, v28, v26
	v_sub_f32_e32 v28, v28, v33
	v_sub_f32_e32 v26, v28, v26
	v_sub_f32_e32 v29, v29, v31
	v_add_f32_e32 v24, v24, v26
	v_add_f32_e32 v24, v29, v24
	v_add_f32_e32 v24, v33, v24
	v_mul_f32_e32 v24, v27, v24
	v_add_f32_e32 v23, v23, v24
	v_add_f32_e32 v24, v30, v23
	v_mul_f32_e32 v26, v24, v24
	v_fmamk_f32 v29, v26, 0x3e9b6dac, v197
	v_sub_f32_e32 v27, v24, v30
	v_ldexp_f32 v28, v24, 1
	v_mul_f32_e32 v24, v24, v26
	v_fmaak_f32 v26, v26, v29, 0x3f2aaada
	v_mul_f32_e32 v24, v24, v26
	v_add_f32_e32 v26, v28, v24
	v_sub_f32_e32 v23, v23, v27
	v_sub_f32_e32 v27, v26, v28
	v_ldexp_f32 v23, v23, 1
	v_sub_f32_e32 v24, v24, v27
	v_add_f32_e32 v23, v23, v24
	v_add_f32_e32 v24, v26, v23
	v_sub_f32_e32 v26, v24, v26
	v_add_f32_e32 v27, v32, v24
	v_sub_f32_e32 v23, v23, v26
	v_sub_f32_e32 v26, v27, v32
	v_sub_f32_e32 v28, v27, v26
	v_sub_f32_e32 v24, v24, v26
	v_add_f32_e32 v26, v25, v23
	v_sub_f32_e32 v28, v32, v28
	v_sub_f32_e32 v29, v26, v25
	v_add_f32_e32 v24, v24, v28
	v_sub_f32_e32 v28, v26, v29
	v_sub_f32_e32 v23, v23, v29
	v_sub_f32_e32 v25, v25, v28
	v_add_f32_e32 v24, v26, v24
	v_add_f32_e32 v23, v23, v25
	v_add_f32_e32 v25, v27, v24
	v_sub_f32_e32 v26, v25, v27
	v_sub_f32_e32 v24, v24, v26
	v_add_f32_e32 v23, v23, v24
	v_add_f32_e32 v23, v25, v23
	v_cmp_neq_f32_e32 vcc, s34, v17
	v_ashrrev_i32_e32 v37, 31, v36
	s_nop 0
	v_cndmask_b32_e32 v23, v214, v23, vcc
	v_cmp_ngt_f32_e32 vcc, -1.0, v17
	s_nop 1
	v_cndmask_b32_e32 v23, v215, v23, vcc
	v_cmp_neq_f32_e32 vcc, -1.0, v17
	s_nop 1
	v_cndmask_b32_e32 v23, v211, v23, vcc
	v_cmp_lt_f32_e64 vcc, |v17|, s37
	s_nop 1
	v_cndmask_b32_e32 v17, v23, v17, vcc
	v_add_f32_e32 v0, v0, v17
	v_xor_b32_e32 v0, 0x80000000, v0
	global_store_dword v[18:19], v0, off
	global_load_dwordx4 v[24:27], v[20:21], off
	global_load_dwordx4 v[28:31], v[20:21], off offset:16
	global_load_dwordx4 v[32:35], v[20:21], off offset:32
	s_nop 0
	global_load_dwordx4 v[18:21], v[20:21], off offset:48
	v_bitop3_b32 v0, v16, s0, 1 bitop3:0xc8
	v_lshlrev_b32_e32 v98, 2, v0
	s_movk_i32 s0, 0xffe
	s_waitcnt vmcnt(2)
	v_pk_add_f32 v[26:27], v[26:27], v[30:31]
	v_pk_add_f32 v[24:25], v[24:25], v[28:29]
	s_waitcnt vmcnt(0)
	v_pk_add_f32 v[20:21], v[34:35], v[20:21]
	v_pk_add_f32 v[18:19], v[32:33], v[18:19]
	v_pk_add_f32 v[20:21], v[26:27], v[20:21]
	v_pk_add_f32 v[18:19], v[24:25], v[18:19]
	s_nop 0
	v_pk_mov_b32 v[24:25], v[18:19], v[20:21] op_sel:[1,0]
	v_mov_b32_e32 v19, v21
	v_pk_add_f32 v[18:19], v[24:25], v[18:19]
	v_lshlrev_b64 v[20:21], 6, v[36:37]
	v_add_f32_e32 v17, v18, v19
	v_fmamk_f32 v17, v17, 0x3a800000, v199
	v_rsq_f32_e32 v17, v17
	v_lshl_add_u64 v[18:19], v[14:15], 0, v[98:99]
	v_fma_f32 v17, v1, v17, v11
	v_mul_f32_e64 v0, |v17|, s40
	v_exp_f32_e32 v23, v0
	v_lshl_add_u64 v[0:1], s[18:19], 0, v[20:21]
	v_max_f32_e64 v17, -v17, 0
	v_add_f32_e32 v24, 1.0, v23
	v_add_f32_e32 v25, -1.0, v24
	v_frexp_mant_f32_e32 v26, v24
	v_cvt_f64_f32_e32 v[20:21], v24
	v_sub_f32_e32 v27, v25, v24
	v_frexp_exp_i32_f64_e32 v20, v[20:21]
	v_cmp_gt_f32_e32 vcc, s35, v26
	v_sub_f32_e32 v25, v23, v25
	v_add_f32_e32 v21, 1.0, v27
	v_subbrev_co_u32_e32 v20, vcc, 0, v20, vcc
	v_add_f32_e32 v21, v25, v21
	v_sub_u32_e32 v25, 0, v20
	v_cvt_f32_i32_e32 v20, v20
	v_ldexp_f32 v24, v24, v25
	v_ldexp_f32 v21, v21, v25
	v_add_f32_e32 v25, -1.0, v24
	v_add_f32_e32 v26, 1.0, v24
	v_add_f32_e32 v27, 1.0, v25
	v_add_f32_e32 v28, -1.0, v26
	v_sub_f32_e32 v27, v24, v27
	v_sub_f32_e32 v24, v24, v28
	v_mul_f32_e32 v28, 0x3f317218, v20
	v_add_f32_e32 v27, v21, v27
	v_add_f32_e32 v21, v21, v24
	v_fma_f32 v24, v20, s36, -v28
	v_add_f32_e32 v29, v25, v27
	v_add_f32_e32 v30, v26, v21
	v_fmac_f32_e32 v24, 0xb102e308, v20
	v_sub_f32_e32 v20, v29, v25
	v_sub_f32_e32 v25, v30, v26
	v_rcp_f32_e32 v26, v30
	v_add_f32_e32 v31, v28, v24
	v_sub_f32_e32 v21, v21, v25
	v_sub_f32_e32 v25, v31, v28
	v_sub_f32_e32 v24, v24, v25
	v_mul_f32_e32 v25, v29, v26
	v_sub_f32_e32 v20, v27, v20
	v_mul_f32_e32 v27, v30, v25
	v_fma_f32 v28, v25, v30, -v27
	v_fmac_f32_e32 v28, v25, v21
	v_add_f32_e32 v32, v27, v28
	v_sub_f32_e32 v33, v29, v32
	v_sub_f32_e32 v27, v32, v27
	v_sub_f32_e32 v29, v29, v33
	v_sub_f32_e32 v27, v27, v28
	v_sub_f32_e32 v28, v29, v32
	v_add_f32_e32 v20, v20, v28
	v_add_f32_e32 v20, v27, v20
	v_add_f32_e32 v27, v33, v20
	v_mul_f32_e32 v28, v26, v27
	v_sub_f32_e32 v29, v33, v27
	v_mul_f32_e32 v32, v30, v28
	v_add_f32_e32 v20, v20, v29
	v_add_f32_e32 v29, v25, v28
	v_fma_f32 v30, v28, v30, -v32
	v_sub_f32_e32 v25, v29, v25
	v_fmac_f32_e32 v30, v28, v21
	v_sub_f32_e32 v21, v28, v25
	v_add_f32_e32 v25, v32, v30
	v_sub_f32_e32 v28, v25, v32
	v_sub_f32_e32 v32, v27, v25
	v_sub_f32_e32 v27, v27, v32
	v_sub_f32_e32 v25, v27, v25
	v_sub_f32_e32 v28, v28, v30
	v_add_f32_e32 v20, v20, v25
	v_add_f32_e32 v20, v28, v20
	v_add_f32_e32 v20, v32, v20
	v_mul_f32_e32 v20, v26, v20
	v_add_f32_e32 v20, v21, v20
	v_add_f32_e32 v21, v29, v20
	v_mul_f32_e32 v25, v21, v21
	v_fmamk_f32 v28, v25, 0x3e9b6dac, v197
	v_sub_f32_e32 v26, v21, v29
	v_ldexp_f32 v27, v21, 1
	v_mul_f32_e32 v21, v21, v25
	v_fmaak_f32 v25, v25, v28, 0x3f2aaada
	v_mul_f32_e32 v21, v21, v25
	v_add_f32_e32 v25, v27, v21
	v_sub_f32_e32 v20, v20, v26
	v_sub_f32_e32 v26, v25, v27
	v_ldexp_f32 v20, v20, 1
	v_sub_f32_e32 v21, v21, v26
	v_add_f32_e32 v20, v20, v21
	v_add_f32_e32 v21, v25, v20
	v_sub_f32_e32 v25, v21, v25
	v_add_f32_e32 v26, v31, v21
	v_sub_f32_e32 v20, v20, v25
	v_sub_f32_e32 v25, v26, v31
	v_sub_f32_e32 v27, v26, v25
	v_sub_f32_e32 v21, v21, v25
	v_add_f32_e32 v25, v24, v20
	v_sub_f32_e32 v27, v31, v27
	v_sub_f32_e32 v28, v25, v24
	v_add_f32_e32 v21, v21, v27
	v_sub_f32_e32 v27, v25, v28
	v_sub_f32_e32 v20, v20, v28
	v_sub_f32_e32 v24, v24, v27
	v_add_f32_e32 v21, v25, v21
	v_add_f32_e32 v20, v20, v24
	v_add_f32_e32 v24, v26, v21
	v_sub_f32_e32 v25, v24, v26
	v_sub_f32_e32 v21, v21, v25
	v_add_f32_e32 v20, v20, v21
	v_add_f32_e32 v20, v24, v20
	v_cmp_neq_f32_e32 vcc, s34, v23
	s_nop 1
	v_cndmask_b32_e32 v20, v214, v20, vcc
	v_cmp_ngt_f32_e32 vcc, -1.0, v23
	s_nop 1
	v_cndmask_b32_e32 v20, v215, v20, vcc
	v_cmp_neq_f32_e32 vcc, -1.0, v23
	s_nop 1
	v_cndmask_b32_e32 v20, v211, v20, vcc
	v_cmp_lt_f32_e64 vcc, |v23|, s37
	s_nop 1
	v_cndmask_b32_e32 v20, v20, v23, vcc
	v_add_f32_e32 v17, v17, v20
	v_xor_b32_e32 v17, 0x80000000, v17
	global_store_dword v[18:19], v17, off
	global_load_dwordx4 v[18:21], v[0:1], off
	s_nop 0
	global_load_dwordx4 v[24:27], v[0:1], off offset:16
	global_load_dwordx4 v[28:31], v[0:1], off offset:32
	global_load_dwordx4 v[32:35], v[0:1], off offset:48
	v_bitop3_b32 v17, v16, s0, 2 bitop3:0xc8
	v_lshlrev_b32_e32 v98, 2, v17
	v_or_b32_e32 v0, 3, v16
	s_movk_i32 s0, 0xfff
	s_waitcnt vmcnt(2)
	v_pk_add_f32 v[20:21], v[20:21], v[26:27]
	v_pk_add_f32 v[18:19], v[18:19], v[24:25]
	s_waitcnt vmcnt(0)
	v_pk_add_f32 v[24:25], v[30:31], v[34:35]
	v_pk_add_f32 v[26:27], v[28:29], v[32:33]
	v_pk_add_f32 v[20:21], v[20:21], v[24:25]
	v_pk_add_f32 v[18:19], v[18:19], v[26:27]
	s_nop 0
	v_pk_mov_b32 v[24:25], v[18:19], v[20:21] op_sel:[1,0]
	v_mov_b32_e32 v19, v21
	v_pk_add_f32 v[18:19], v[24:25], v[18:19]
	s_nop 0
	v_add_f32_e32 v1, v18, v19
	v_fmamk_f32 v1, v1, 0x3a800000, v199
	v_rsq_f32_e32 v18, v1
	v_ashrrev_i32_e32 v1, 31, v0
	v_lshlrev_b64 v[0:1], 6, v[0:1]
	v_lshl_add_u64 v[0:1], s[18:19], 0, v[0:1]
	v_fma_f32 v2, v2, v18, v11
	v_mul_f32_e64 v17, |v2|, s40
	v_exp_f32_e32 v17, v17
	v_max_f32_e64 v2, -v2, 0
	v_lshl_add_u64 v[18:19], v[14:15], 0, v[98:99]
	v_add_f32_e32 v23, 1.0, v17
	v_add_f32_e32 v24, -1.0, v23
	v_frexp_mant_f32_e32 v25, v23
	v_cvt_f64_f32_e32 v[20:21], v23
	v_sub_f32_e32 v26, v24, v23
	v_frexp_exp_i32_f64_e32 v20, v[20:21]
	v_cmp_gt_f32_e32 vcc, s35, v25
	v_sub_f32_e32 v24, v17, v24
	v_add_f32_e32 v21, 1.0, v26
	v_subbrev_co_u32_e32 v20, vcc, 0, v20, vcc
	v_add_f32_e32 v21, v24, v21
	v_sub_u32_e32 v24, 0, v20
	v_cvt_f32_i32_e32 v20, v20
	v_ldexp_f32 v23, v23, v24
	v_ldexp_f32 v21, v21, v24
	v_add_f32_e32 v24, -1.0, v23
	v_add_f32_e32 v25, 1.0, v23
	v_add_f32_e32 v26, 1.0, v24
	v_add_f32_e32 v27, -1.0, v25
	v_sub_f32_e32 v26, v23, v26
	v_sub_f32_e32 v23, v23, v27
	v_mul_f32_e32 v27, 0x3f317218, v20
	v_add_f32_e32 v26, v21, v26
	v_add_f32_e32 v21, v21, v23
	v_fma_f32 v23, v20, s36, -v27
	v_add_f32_e32 v28, v24, v26
	v_add_f32_e32 v29, v25, v21
	v_fmac_f32_e32 v23, 0xb102e308, v20
	v_sub_f32_e32 v20, v28, v24
	v_sub_f32_e32 v24, v29, v25
	v_rcp_f32_e32 v25, v29
	v_add_f32_e32 v30, v27, v23
	v_sub_f32_e32 v21, v21, v24
	v_sub_f32_e32 v24, v30, v27
	v_sub_f32_e32 v23, v23, v24
	v_mul_f32_e32 v24, v28, v25
	v_sub_f32_e32 v20, v26, v20
	v_mul_f32_e32 v26, v29, v24
	v_fma_f32 v27, v24, v29, -v26
	v_fmac_f32_e32 v27, v24, v21
	v_add_f32_e32 v31, v26, v27
	v_sub_f32_e32 v32, v28, v31
	v_sub_f32_e32 v26, v31, v26
	v_sub_f32_e32 v28, v28, v32
	v_sub_f32_e32 v26, v26, v27
	v_sub_f32_e32 v27, v28, v31
	v_add_f32_e32 v20, v20, v27
	v_add_f32_e32 v20, v26, v20
	v_add_f32_e32 v26, v32, v20
	v_mul_f32_e32 v27, v25, v26
	v_sub_f32_e32 v28, v32, v26
	v_mul_f32_e32 v31, v29, v27
	v_add_f32_e32 v20, v20, v28
	v_add_f32_e32 v28, v24, v27
	v_fma_f32 v29, v27, v29, -v31
	v_sub_f32_e32 v24, v28, v24
	v_fmac_f32_e32 v29, v27, v21
	v_sub_f32_e32 v21, v27, v24
	v_add_f32_e32 v24, v31, v29
	v_sub_f32_e32 v27, v24, v31
	v_sub_f32_e32 v31, v26, v24
	v_sub_f32_e32 v26, v26, v31
	v_sub_f32_e32 v24, v26, v24
	v_sub_f32_e32 v27, v27, v29
	v_add_f32_e32 v20, v20, v24
	v_add_f32_e32 v20, v27, v20
	v_add_f32_e32 v20, v31, v20
	v_mul_f32_e32 v20, v25, v20
	v_add_f32_e32 v20, v21, v20
	v_add_f32_e32 v21, v28, v20
	v_mul_f32_e32 v24, v21, v21
	v_fmamk_f32 v27, v24, 0x3e9b6dac, v197
	v_sub_f32_e32 v25, v21, v28
	v_ldexp_f32 v26, v21, 1
	v_mul_f32_e32 v21, v21, v24
	v_fmaak_f32 v24, v24, v27, 0x3f2aaada
	v_mul_f32_e32 v21, v21, v24
	v_add_f32_e32 v24, v26, v21
	v_sub_f32_e32 v20, v20, v25
	v_sub_f32_e32 v25, v24, v26
	v_ldexp_f32 v20, v20, 1
	v_sub_f32_e32 v21, v21, v25
	v_add_f32_e32 v20, v20, v21
	v_add_f32_e32 v21, v24, v20
	v_sub_f32_e32 v24, v21, v24
	v_add_f32_e32 v25, v30, v21
	v_sub_f32_e32 v20, v20, v24
	v_sub_f32_e32 v24, v25, v30
	v_sub_f32_e32 v26, v25, v24
	v_sub_f32_e32 v21, v21, v24
	v_add_f32_e32 v24, v23, v20
	v_sub_f32_e32 v26, v30, v26
	v_sub_f32_e32 v27, v24, v23
	v_add_f32_e32 v21, v21, v26
	v_sub_f32_e32 v26, v24, v27
	v_sub_f32_e32 v20, v20, v27
	v_sub_f32_e32 v23, v23, v26
	v_add_f32_e32 v21, v24, v21
	v_add_f32_e32 v20, v20, v23
	v_add_f32_e32 v23, v25, v21
	v_sub_f32_e32 v24, v23, v25
	v_sub_f32_e32 v21, v21, v24
	v_add_f32_e32 v20, v20, v21
	v_add_f32_e32 v20, v23, v20
	v_cmp_neq_f32_e32 vcc, s34, v17
	s_nop 1
	v_cndmask_b32_e32 v20, v214, v20, vcc
	v_cmp_ngt_f32_e32 vcc, -1.0, v17
	s_nop 1
	v_cndmask_b32_e32 v20, v215, v20, vcc
	v_cmp_neq_f32_e32 vcc, -1.0, v17
	s_nop 1
	v_cndmask_b32_e32 v20, v211, v20, vcc
	v_cmp_lt_f32_e64 vcc, |v17|, s37
	s_nop 1
	v_cndmask_b32_e32 v17, v20, v17, vcc
	v_add_f32_e32 v2, v2, v17
	v_xor_b32_e32 v2, 0x80000000, v2
	global_store_dword v[18:19], v2, off
	global_load_dwordx4 v[18:21], v[0:1], off
	s_nop 0
	global_load_dwordx4 v[24:27], v[0:1], off offset:16
	global_load_dwordx4 v[28:31], v[0:1], off offset:32
	global_load_dwordx4 v[32:35], v[0:1], off offset:48
	s_waitcnt vmcnt(2)
	v_pk_add_f32 v[0:1], v[20:21], v[26:27]
	v_pk_add_f32 v[18:19], v[18:19], v[24:25]
	s_waitcnt vmcnt(0)
	v_pk_add_f32 v[20:21], v[30:31], v[34:35]
	v_pk_add_f32 v[24:25], v[28:29], v[32:33]
	v_pk_add_f32 v[0:1], v[0:1], v[20:21]
	v_pk_add_f32 v[18:19], v[18:19], v[24:25]
	s_nop 0
	v_pk_mov_b32 v[20:21], v[18:19], v[0:1] op_sel:[1,0]
	v_mov_b32_e32 v19, v1
	v_pk_add_f32 v[0:1], v[20:21], v[18:19]
	s_nop 0
	v_add_f32_e32 v0, v0, v1
	v_fmamk_f32 v0, v0, 0x3a800000, v199
	v_rsq_f32_e32 v0, v0
	s_nop 0
	v_fmac_f32_e32 v11, v3, v0
	v_mul_f32_e64 v0, |v11|, s40
	v_exp_f32_e32 v2, v0
	v_bitop3_b32 v0, v16, s0, 3 bitop3:0xc8
	v_max_f32_e64 v3, -v11, 0
	v_lshlrev_b32_e32 v98, 2, v0
	v_add_f32_e32 v11, 1.0, v2
	v_add_f32_e32 v16, -1.0, v11
	v_frexp_mant_f32_e32 v17, v11
	v_cvt_f64_f32_e32 v[0:1], v11
	v_sub_f32_e32 v18, v16, v11
	v_frexp_exp_i32_f64_e32 v0, v[0:1]
	v_cmp_gt_f32_e32 vcc, s35, v17
	v_sub_f32_e32 v16, v2, v16
	v_add_f32_e32 v1, 1.0, v18
	v_subbrev_co_u32_e32 v0, vcc, 0, v0, vcc
	v_add_f32_e32 v1, v16, v1
	v_sub_u32_e32 v16, 0, v0
	v_cvt_f32_i32_e32 v0, v0
	v_ldexp_f32 v11, v11, v16
	v_ldexp_f32 v1, v1, v16
	v_add_f32_e32 v16, -1.0, v11
	v_add_f32_e32 v17, 1.0, v11
	v_add_f32_e32 v18, 1.0, v16
	v_add_f32_e32 v19, -1.0, v17
	v_sub_f32_e32 v18, v11, v18
	v_sub_f32_e32 v11, v11, v19
	v_mul_f32_e32 v19, 0x3f317218, v0
	v_add_f32_e32 v18, v1, v18
	v_add_f32_e32 v1, v1, v11
	v_fma_f32 v11, v0, s36, -v19
	v_add_f32_e32 v20, v16, v18
	v_add_f32_e32 v21, v17, v1
	v_fmac_f32_e32 v11, 0xb102e308, v0
	v_sub_f32_e32 v0, v20, v16
	v_sub_f32_e32 v16, v21, v17
	v_rcp_f32_e32 v17, v21
	v_add_f32_e32 v23, v19, v11
	v_sub_f32_e32 v1, v1, v16
	v_sub_f32_e32 v16, v23, v19
	v_sub_f32_e32 v11, v11, v16
	v_mul_f32_e32 v16, v20, v17
	v_sub_f32_e32 v0, v18, v0
	v_mul_f32_e32 v18, v21, v16
	v_fma_f32 v19, v16, v21, -v18
	v_fmac_f32_e32 v19, v16, v1
	v_add_f32_e32 v24, v18, v19
	v_sub_f32_e32 v25, v20, v24
	v_sub_f32_e32 v18, v24, v18
	v_sub_f32_e32 v20, v20, v25
	v_sub_f32_e32 v18, v18, v19
	v_sub_f32_e32 v19, v20, v24
	v_add_f32_e32 v0, v0, v19
	v_add_f32_e32 v0, v18, v0
	v_add_f32_e32 v18, v25, v0
	v_mul_f32_e32 v19, v17, v18
	v_sub_f32_e32 v20, v25, v18
	v_mul_f32_e32 v24, v21, v19
	v_add_f32_e32 v0, v0, v20
	v_add_f32_e32 v20, v16, v19
	v_fma_f32 v21, v19, v21, -v24
	v_sub_f32_e32 v16, v20, v16
	v_fmac_f32_e32 v21, v19, v1
	v_sub_f32_e32 v1, v19, v16
	v_add_f32_e32 v16, v24, v21
	v_sub_f32_e32 v19, v16, v24
	v_sub_f32_e32 v24, v18, v16
	v_sub_f32_e32 v18, v18, v24
	v_sub_f32_e32 v16, v18, v16
	v_sub_f32_e32 v19, v19, v21
	v_add_f32_e32 v0, v0, v16
	v_add_f32_e32 v0, v19, v0
	v_add_f32_e32 v0, v24, v0
	v_mul_f32_e32 v0, v17, v0
	v_add_f32_e32 v0, v1, v0
	v_add_f32_e32 v1, v20, v0
	v_mul_f32_e32 v16, v1, v1
	v_fmamk_f32 v19, v16, 0x3e9b6dac, v197
	v_sub_f32_e32 v17, v1, v20
	v_ldexp_f32 v18, v1, 1
	v_mul_f32_e32 v1, v1, v16
	v_fmaak_f32 v16, v16, v19, 0x3f2aaada
	v_mul_f32_e32 v1, v1, v16
	v_add_f32_e32 v16, v18, v1
	v_sub_f32_e32 v0, v0, v17
	v_sub_f32_e32 v17, v16, v18
	v_ldexp_f32 v0, v0, 1
	v_sub_f32_e32 v1, v1, v17
	v_add_f32_e32 v0, v0, v1
	v_add_f32_e32 v1, v16, v0
	v_sub_f32_e32 v16, v1, v16
	v_add_f32_e32 v17, v23, v1
	v_sub_f32_e32 v0, v0, v16
	v_sub_f32_e32 v16, v17, v23
	v_sub_f32_e32 v18, v17, v16
	v_sub_f32_e32 v1, v1, v16
	v_add_f32_e32 v16, v11, v0
	v_sub_f32_e32 v18, v23, v18
	v_sub_f32_e32 v19, v16, v11
	v_add_f32_e32 v1, v1, v18
	v_sub_f32_e32 v18, v16, v19
	v_sub_f32_e32 v0, v0, v19
	v_sub_f32_e32 v11, v11, v18
	v_add_f32_e32 v1, v16, v1
	v_add_f32_e32 v0, v0, v11
	v_add_f32_e32 v11, v17, v1
	v_sub_f32_e32 v16, v11, v17
	v_sub_f32_e32 v1, v1, v16
	v_add_f32_e32 v0, v0, v1
	v_add_f32_e32 v0, v11, v0
	v_cmp_neq_f32_e32 vcc, s34, v2
	s_nop 1
	v_cndmask_b32_e32 v0, v214, v0, vcc
	v_cmp_ngt_f32_e32 vcc, -1.0, v2
	s_nop 1
	v_cndmask_b32_e32 v0, v215, v0, vcc
	v_cmp_neq_f32_e32 vcc, -1.0, v2
	s_nop 1
	v_cndmask_b32_e32 v0, v211, v0, vcc
	v_cmp_lt_f32_e64 vcc, |v2|, s37
	s_nop 1
	v_cndmask_b32_e32 v0, v0, v2, vcc
	v_add_f32_e32 v0, v3, v0
	v_xor_b32_e32 v2, 0x80000000, v0
	v_lshl_add_u64 v[0:1], v[14:15], 0, v[98:99]
	global_store_dword v[0:1], v2, off
	s_branch .LBB0_216
